# initial row pass mostly moved to the workgroups that have no fold unit (slot between grid barriers 1 and 2)
# speedup vs baseline: 1.0022x; 1.0022x over previous
.LBB0_24:
	s_or_b64 exec, exec, s[44:45]
	s_add_u32 s30, s30, s80
	s_addc_u32 s31, s31, s81
	s_add_u32 s8, s8, s28
	s_addc_u32 s9, s9, s29
	s_cmp_gt_i32 s30, 0x7ff
	s_cbranch_scc1 .LBB0_29

.LBB0_109:
	s_cmpk_lg_i32 s54, 0x100
	s_cbranch_scc1 .Lp01_fb
	s_add_u32 s66, s42, 0x60d3c00
	s_addc_u32 s67, s43, 0
	v_mov_b32_e32 v20, 0
	global_load_dwordx4 v[24:27], v20, s[66:67] sc1
	global_load_dwordx4 v[28:31], v20, s[66:67] offset:16 sc1
	s_waitcnt vmcnt(0)
	v_readfirstlane_b32 s66, v24
	s_bcnt1_i32_b32 s66, s66
	s_cmp_lg_u32 s66, 1
	s_cbranch_scc1 .Lp01_fb
	v_readfirstlane_b32 s66, v25
	s_bcnt1_i32_b32 s66, s66
	s_cmp_lg_u32 s66, 1
	s_cbranch_scc1 .Lp01_fb
	v_readfirstlane_b32 s66, v26
	s_bcnt1_i32_b32 s66, s66
	s_cmp_lg_u32 s66, 1
	s_cbranch_scc1 .Lp01_fb
	v_readfirstlane_b32 s66, v27
	s_bcnt1_i32_b32 s66, s66
	s_cmp_lg_u32 s66, 1
	s_cbranch_scc1 .Lp01_fb
	v_readfirstlane_b32 s66, v28
	s_bcnt1_i32_b32 s66, s66
	s_cmp_lg_u32 s66, 1
	s_cbranch_scc1 .Lp01_fb
	v_readfirstlane_b32 s66, v29
	s_bcnt1_i32_b32 s66, s66
	s_cmp_lg_u32 s66, 1
	s_cbranch_scc1 .Lp01_fb
	v_readfirstlane_b32 s66, v30
	s_bcnt1_i32_b32 s66, s66
	s_cmp_lg_u32 s66, 1
	s_cbranch_scc1 .Lp01_fb
	v_readfirstlane_b32 s66, v31
	s_bcnt1_i32_b32 s66, s66
	s_cmp_lg_u32 s66, 1
	s_cbranch_scc1 .Lp01_fb
	s_mov_b32 s32, 1
	s_lshr_b32 s56, s10, 3
	s_cmp_lt_u32 s56, 0x80
	s_cbranch_scc1 .Lp01_dec_done
	v_mov_b32_e32 v136, 0x358637bd
	v_mov_b32_e32 v137, 0
	v_lshlrev_b32_e32 v138, 4, v190
	v_xor_b32_e32 v130, 1, v190
	v_lshlrev_b32_e32 v130, 2, v130
	v_xor_b32_e32 v131, 2, v190
	v_lshlrev_b32_e32 v131, 2, v131
	v_xor_b32_e32 v132, 4, v190
	v_lshlrev_b32_e32 v132, 2, v132
	v_xor_b32_e32 v133, 8, v190
	v_lshlrev_b32_e32 v133, 2, v133
	v_xor_b32_e32 v134, 16, v190
	v_lshlrev_b32_e32 v134, 2, v134
	v_xor_b32_e32 v135, 32, v190
	v_lshlrev_b32_e32 v135, 2, v135
	s_add_i32 s56, s10, 0x400
	s_mov_b32 s57, 2
.Lp01_pre_loop:
	s_mov_b32 s66, s56
	s_add_i32 s97, s56, 0x400
	s_add_i32 s98, s56, 0x800
	s_add_i32 s96, s56, 0xc00
	s_add_i32 s99, s56, 0x1000
	s_add_i32 s58, s56, 0x1400
	s_cmp_lt_u32 s66, 0x8000
	s_cselect_b32 s68, s12, s14
	s_cselect_b32 s69, s13, s15
	s_cselect_b32 s67, 0, 0x8000
	s_sub_u32 s67, s66, s67
	s_lshl_b32 s67, s67, 12
	s_add_u32 s68, s68, s67
	s_addc_u32 s69, s69, 0
	global_load_dwordx4 v[18:21], v138, s[68:69] offset:0 nt
	global_load_dwordx4 v[22:25], v138, s[68:69] offset:1024 nt
	global_load_dwordx4 v[26:29], v138, s[68:69] offset:2048 nt
	global_load_dwordx4 v[30:33], v138, s[68:69] offset:3072 nt
	s_cmp_lt_u32 s97, 0x8000
	s_cselect_b32 s70, s12, s14
	s_cselect_b32 s71, s13, s15
	s_cselect_b32 s67, 0, 0x8000
	s_sub_u32 s67, s97, s67
	s_lshl_b32 s67, s67, 12
	s_add_u32 s70, s70, s67
	s_addc_u32 s71, s71, 0
	global_load_dwordx4 v[34:37], v138, s[70:71] offset:0 nt
	global_load_dwordx4 v[38:41], v138, s[70:71] offset:1024 nt
	global_load_dwordx4 v[42:45], v138, s[70:71] offset:2048 nt
	global_load_dwordx4 v[46:49], v138, s[70:71] offset:3072 nt
	s_cmp_lt_u32 s98, 0x8000
	s_cselect_b32 s72, s12, s14
	s_cselect_b32 s73, s13, s15
	s_cselect_b32 s67, 0, 0x8000
	s_sub_u32 s67, s98, s67
	s_lshl_b32 s67, s67, 12
	s_add_u32 s72, s72, s67
	s_addc_u32 s73, s73, 0
	global_load_dwordx4 v[50:53], v138, s[72:73] offset:0 nt
	global_load_dwordx4 v[54:57], v138, s[72:73] offset:1024 nt
	global_load_dwordx4 v[58:61], v138, s[72:73] offset:2048 nt
	global_load_dwordx4 v[62:65], v138, s[72:73] offset:3072 nt
	s_cmp_lt_u32 s96, 0x8000
	s_cselect_b32 s16, s12, s14
	s_cselect_b32 s17, s13, s15
	s_cselect_b32 s67, 0, 0x8000
	s_sub_u32 s67, s96, s67
	s_lshl_b32 s67, s67, 12
	s_add_u32 s16, s16, s67
	s_addc_u32 s17, s17, 0
	global_load_dwordx4 v[66:69], v138, s[16:17] offset:0 nt
	global_load_dwordx4 v[70:73], v138, s[16:17] offset:1024 nt
	global_load_dwordx4 v[74:77], v138, s[16:17] offset:2048 nt
	global_load_dwordx4 v[78:81], v138, s[16:17] offset:3072 nt
	s_cmp_lt_u32 s99, 0x8000
	s_cselect_b32 s18, s12, s14
	s_cselect_b32 s19, s13, s15
	s_cselect_b32 s67, 0, 0x8000
	s_sub_u32 s67, s99, s67
	s_lshl_b32 s67, s67, 12
	s_add_u32 s18, s18, s67
	s_addc_u32 s19, s19, 0
	global_load_dwordx4 v[82:85], v138, s[18:19] offset:0 nt
	global_load_dwordx4 v[86:89], v138, s[18:19] offset:1024 nt
	global_load_dwordx4 v[90:93], v138, s[18:19] offset:2048 nt
	global_load_dwordx4 v[94:97], v138, s[18:19] offset:3072 nt
	s_cmp_lt_u32 s58, 0x8000
	s_cselect_b32 s36, s12, s14
	s_cselect_b32 s37, s13, s15
	s_cselect_b32 s67, 0, 0x8000
	s_sub_u32 s67, s58, s67
	s_lshl_b32 s67, s67, 12
	s_add_u32 s36, s36, s67
	s_addc_u32 s37, s37, 0
	global_load_dwordx4 v[98:101], v138, s[36:37] offset:0 nt
	global_load_dwordx4 v[102:105], v138, s[36:37] offset:1024 nt
	global_load_dwordx4 v[106:109], v138, s[36:37] offset:2048 nt
	global_load_dwordx4 v[110:113], v138, s[36:37] offset:3072 nt
	s_lshl_b32 s67, s66, 11
	s_add_u32 s86, s42, s67
	s_addc_u32 s87, s43, 0
	s_waitcnt vmcnt(20)
	v_mul_f32_e32 v114, v19, v19
	v_mul_f32_e32 v115, v23, v23
	v_mul_f32_e32 v116, v27, v27
	v_fmac_f32_e32 v114, v18, v18
	v_fmac_f32_e32 v115, v22, v22
	v_mul_f32_e32 v117, v31, v31
	v_fmac_f32_e32 v116, v26, v26
	v_fmac_f32_e32 v114, v20, v20
	v_fmac_f32_e32 v115, v24, v24
	v_fmac_f32_e32 v117, v30, v30
	v_fmac_f32_e32 v116, v28, v28
	v_fmac_f32_e32 v114, v21, v21
	v_fmac_f32_e32 v115, v25, v25
	v_fmac_f32_e32 v117, v32, v32
	v_fmac_f32_e32 v116, v29, v29
	v_add_f32_e32 v114, v114, v115
	v_fmac_f32_e32 v117, v33, v33
	v_add_f32_e32 v114, v114, v116
	v_add_f32_e32 v118, v114, v117
	v_cvt_pk_bf16_f32 v18, v18, v19
	v_cvt_pk_bf16_f32 v19, v20, v21
	v_cvt_pk_bf16_f32 v20, v22, v23
	v_cvt_pk_bf16_f32 v21, v24, v25
	v_cvt_pk_bf16_f32 v22, v26, v27
	v_cvt_pk_bf16_f32 v23, v28, v29
	v_cvt_pk_bf16_f32 v24, v30, v31
	v_cvt_pk_bf16_f32 v25, v32, v33
	global_store_dwordx2 v188, v[18:19], s[86:87] offset:0
	global_store_dwordx2 v188, v[20:21], s[86:87] offset:512
	global_store_dwordx2 v188, v[22:23], s[86:87] offset:1024
	global_store_dwordx2 v188, v[24:25], s[86:87] offset:1536
	s_lshl_b32 s67, s97, 11
	s_add_u32 s88, s42, s67
	s_addc_u32 s89, s43, 0
	s_waitcnt vmcnt(20)
	v_mul_f32_e32 v114, v35, v35
	v_mul_f32_e32 v115, v39, v39
	v_mul_f32_e32 v116, v43, v43
	v_fmac_f32_e32 v114, v34, v34
	v_fmac_f32_e32 v115, v38, v38
	v_mul_f32_e32 v117, v47, v47
	v_fmac_f32_e32 v116, v42, v42
	v_fmac_f32_e32 v114, v36, v36
	v_fmac_f32_e32 v115, v40, v40
	v_fmac_f32_e32 v117, v46, v46
	v_fmac_f32_e32 v116, v44, v44
	v_fmac_f32_e32 v114, v37, v37
	v_fmac_f32_e32 v115, v41, v41
	v_fmac_f32_e32 v117, v48, v48
	v_fmac_f32_e32 v116, v45, v45
	v_add_f32_e32 v114, v114, v115
	v_fmac_f32_e32 v117, v49, v49
	v_add_f32_e32 v114, v114, v116
	v_add_f32_e32 v119, v114, v117
	v_cvt_pk_bf16_f32 v34, v34, v35
	v_cvt_pk_bf16_f32 v35, v36, v37
	v_cvt_pk_bf16_f32 v36, v38, v39
	v_cvt_pk_bf16_f32 v37, v40, v41
	v_cvt_pk_bf16_f32 v38, v42, v43
	v_cvt_pk_bf16_f32 v39, v44, v45
	v_cvt_pk_bf16_f32 v40, v46, v47
	v_cvt_pk_bf16_f32 v41, v48, v49
	global_store_dwordx2 v188, v[34:35], s[88:89] offset:0
	global_store_dwordx2 v188, v[36:37], s[88:89] offset:512
	global_store_dwordx2 v188, v[38:39], s[88:89] offset:1024
	global_store_dwordx2 v188, v[40:41], s[88:89] offset:1536
	s_lshl_b32 s67, s98, 11
	s_add_u32 s90, s42, s67
	s_addc_u32 s91, s43, 0
	s_waitcnt vmcnt(20)
	v_mul_f32_e32 v114, v51, v51
	v_mul_f32_e32 v115, v55, v55
	v_mul_f32_e32 v116, v59, v59
	v_fmac_f32_e32 v114, v50, v50
	v_fmac_f32_e32 v115, v54, v54
	v_mul_f32_e32 v117, v63, v63
	v_fmac_f32_e32 v116, v58, v58
	v_fmac_f32_e32 v114, v52, v52
	v_fmac_f32_e32 v115, v56, v56
	v_fmac_f32_e32 v117, v62, v62
	v_fmac_f32_e32 v116, v60, v60
	v_fmac_f32_e32 v114, v53, v53
	v_fmac_f32_e32 v115, v57, v57
	v_fmac_f32_e32 v117, v64, v64
	v_fmac_f32_e32 v116, v61, v61
	v_add_f32_e32 v114, v114, v115
	v_fmac_f32_e32 v117, v65, v65
	v_add_f32_e32 v114, v114, v116
	v_add_f32_e32 v120, v114, v117
	v_cvt_pk_bf16_f32 v50, v50, v51
	v_cvt_pk_bf16_f32 v51, v52, v53
	v_cvt_pk_bf16_f32 v52, v54, v55
	v_cvt_pk_bf16_f32 v53, v56, v57
	v_cvt_pk_bf16_f32 v54, v58, v59
	v_cvt_pk_bf16_f32 v55, v60, v61
	v_cvt_pk_bf16_f32 v56, v62, v63
	v_cvt_pk_bf16_f32 v57, v64, v65
	global_store_dwordx2 v188, v[50:51], s[90:91] offset:0
	global_store_dwordx2 v188, v[52:53], s[90:91] offset:512
	global_store_dwordx2 v188, v[54:55], s[90:91] offset:1024
	global_store_dwordx2 v188, v[56:57], s[90:91] offset:1536
	s_lshl_b32 s67, s96, 11
	s_add_u32 s46, s42, s67
	s_addc_u32 s47, s43, 0
	s_waitcnt vmcnt(20)
	v_mul_f32_e32 v114, v67, v67
	v_mul_f32_e32 v115, v71, v71
	v_mul_f32_e32 v116, v75, v75
	v_fmac_f32_e32 v114, v66, v66
	v_fmac_f32_e32 v115, v70, v70
	v_mul_f32_e32 v117, v79, v79
	v_fmac_f32_e32 v116, v74, v74
	v_fmac_f32_e32 v114, v68, v68
	v_fmac_f32_e32 v115, v72, v72
	v_fmac_f32_e32 v117, v78, v78
	v_fmac_f32_e32 v116, v76, v76
	v_fmac_f32_e32 v114, v69, v69
	v_fmac_f32_e32 v115, v73, v73
	v_fmac_f32_e32 v117, v80, v80
	v_fmac_f32_e32 v116, v77, v77
	v_add_f32_e32 v114, v114, v115
	v_fmac_f32_e32 v117, v81, v81
	v_add_f32_e32 v114, v114, v116
	v_add_f32_e32 v121, v114, v117
	v_cvt_pk_bf16_f32 v66, v66, v67
	v_cvt_pk_bf16_f32 v67, v68, v69
	v_cvt_pk_bf16_f32 v68, v70, v71
	v_cvt_pk_bf16_f32 v69, v72, v73
	v_cvt_pk_bf16_f32 v70, v74, v75
	v_cvt_pk_bf16_f32 v71, v76, v77
	v_cvt_pk_bf16_f32 v72, v78, v79
	v_cvt_pk_bf16_f32 v73, v80, v81
	global_store_dwordx2 v188, v[66:67], s[46:47] offset:0
	global_store_dwordx2 v188, v[68:69], s[46:47] offset:512
	global_store_dwordx2 v188, v[70:71], s[46:47] offset:1024
	global_store_dwordx2 v188, v[72:73], s[46:47] offset:1536
	s_lshl_b32 s67, s99, 11
	s_add_u32 s50, s42, s67
	s_addc_u32 s51, s43, 0
	s_waitcnt vmcnt(20)
	v_mul_f32_e32 v114, v83, v83
	v_mul_f32_e32 v115, v87, v87
	v_mul_f32_e32 v116, v91, v91
	v_fmac_f32_e32 v114, v82, v82
	v_fmac_f32_e32 v115, v86, v86
	v_mul_f32_e32 v117, v95, v95
	v_fmac_f32_e32 v116, v90, v90
	v_fmac_f32_e32 v114, v84, v84
	v_fmac_f32_e32 v115, v88, v88
	v_fmac_f32_e32 v117, v94, v94
	v_fmac_f32_e32 v116, v92, v92
	v_fmac_f32_e32 v114, v85, v85
	v_fmac_f32_e32 v115, v89, v89
	v_fmac_f32_e32 v117, v96, v96
	v_fmac_f32_e32 v116, v93, v93
	v_add_f32_e32 v114, v114, v115
	v_fmac_f32_e32 v117, v97, v97
	v_add_f32_e32 v114, v114, v116
	v_add_f32_e32 v122, v114, v117
	v_cvt_pk_bf16_f32 v82, v82, v83
	v_cvt_pk_bf16_f32 v83, v84, v85
	v_cvt_pk_bf16_f32 v84, v86, v87
	v_cvt_pk_bf16_f32 v85, v88, v89
	v_cvt_pk_bf16_f32 v86, v90, v91
	v_cvt_pk_bf16_f32 v87, v92, v93
	v_cvt_pk_bf16_f32 v88, v94, v95
	v_cvt_pk_bf16_f32 v89, v96, v97
	global_store_dwordx2 v188, v[82:83], s[50:51] offset:0
	global_store_dwordx2 v188, v[84:85], s[50:51] offset:512
	global_store_dwordx2 v188, v[86:87], s[50:51] offset:1024
	global_store_dwordx2 v188, v[88:89], s[50:51] offset:1536
	s_lshl_b32 s67, s58, 11
	s_add_u32 s52, s42, s67
	s_addc_u32 s53, s43, 0
	s_waitcnt vmcnt(20)
	v_mul_f32_e32 v114, v99, v99
	v_mul_f32_e32 v115, v103, v103
	v_mul_f32_e32 v116, v107, v107
	v_fmac_f32_e32 v114, v98, v98
	v_fmac_f32_e32 v115, v102, v102
	v_mul_f32_e32 v117, v111, v111
	v_fmac_f32_e32 v116, v106, v106
	v_fmac_f32_e32 v114, v100, v100
	v_fmac_f32_e32 v115, v104, v104
	v_fmac_f32_e32 v117, v110, v110
	v_fmac_f32_e32 v116, v108, v108
	v_fmac_f32_e32 v114, v101, v101
	v_fmac_f32_e32 v115, v105, v105
	v_fmac_f32_e32 v117, v112, v112
	v_fmac_f32_e32 v116, v109, v109
	v_add_f32_e32 v114, v114, v115
	v_fmac_f32_e32 v117, v113, v113
	v_add_f32_e32 v114, v114, v116
	v_add_f32_e32 v123, v114, v117
	v_cvt_pk_bf16_f32 v98, v98, v99
	v_cvt_pk_bf16_f32 v99, v100, v101
	v_cvt_pk_bf16_f32 v100, v102, v103
	v_cvt_pk_bf16_f32 v101, v104, v105
	v_cvt_pk_bf16_f32 v102, v106, v107
	v_cvt_pk_bf16_f32 v103, v108, v109
	v_cvt_pk_bf16_f32 v104, v110, v111
	v_cvt_pk_bf16_f32 v105, v112, v113
	global_store_dwordx2 v188, v[98:99], s[52:53] offset:0
	global_store_dwordx2 v188, v[100:101], s[52:53] offset:512
	global_store_dwordx2 v188, v[102:103], s[52:53] offset:1024
	global_store_dwordx2 v188, v[104:105], s[52:53] offset:1536
	ds_bpermute_b32 v124, v130, v118
	ds_bpermute_b32 v125, v130, v119
	ds_bpermute_b32 v126, v130, v120
	ds_bpermute_b32 v127, v130, v121
	ds_bpermute_b32 v128, v130, v122
	ds_bpermute_b32 v129, v130, v123
	s_waitcnt lgkmcnt(0)
	v_add_f32_e32 v118, v118, v124
	v_add_f32_e32 v119, v119, v125
	v_add_f32_e32 v120, v120, v126
	v_add_f32_e32 v121, v121, v127
	v_add_f32_e32 v122, v122, v128
	v_add_f32_e32 v123, v123, v129
	ds_bpermute_b32 v124, v131, v118
	ds_bpermute_b32 v125, v131, v119
	ds_bpermute_b32 v126, v131, v120
	ds_bpermute_b32 v127, v131, v121
	ds_bpermute_b32 v128, v131, v122
	ds_bpermute_b32 v129, v131, v123
	s_waitcnt lgkmcnt(0)
	v_add_f32_e32 v118, v118, v124
	v_add_f32_e32 v119, v119, v125
	v_add_f32_e32 v120, v120, v126
	v_add_f32_e32 v121, v121, v127
	v_add_f32_e32 v122, v122, v128
	v_add_f32_e32 v123, v123, v129
	ds_bpermute_b32 v124, v132, v118
	ds_bpermute_b32 v125, v132, v119
	ds_bpermute_b32 v126, v132, v120
	ds_bpermute_b32 v127, v132, v121
	ds_bpermute_b32 v128, v132, v122
	ds_bpermute_b32 v129, v132, v123
	s_waitcnt lgkmcnt(0)
	v_add_f32_e32 v118, v118, v124
	v_add_f32_e32 v119, v119, v125
	v_add_f32_e32 v120, v120, v126
	v_add_f32_e32 v121, v121, v127
	v_add_f32_e32 v122, v122, v128
	v_add_f32_e32 v123, v123, v129
	ds_bpermute_b32 v124, v133, v118
	ds_bpermute_b32 v125, v133, v119
	ds_bpermute_b32 v126, v133, v120
	ds_bpermute_b32 v127, v133, v121
	ds_bpermute_b32 v128, v133, v122
	ds_bpermute_b32 v129, v133, v123
	s_waitcnt lgkmcnt(0)
	v_add_f32_e32 v118, v118, v124
	v_add_f32_e32 v119, v119, v125
	v_add_f32_e32 v120, v120, v126
	v_add_f32_e32 v121, v121, v127
	v_add_f32_e32 v122, v122, v128
	v_add_f32_e32 v123, v123, v129
	ds_bpermute_b32 v124, v134, v118
	ds_bpermute_b32 v125, v134, v119
	ds_bpermute_b32 v126, v134, v120
	ds_bpermute_b32 v127, v134, v121
	ds_bpermute_b32 v128, v134, v122
	ds_bpermute_b32 v129, v134, v123
	s_waitcnt lgkmcnt(0)
	v_add_f32_e32 v118, v118, v124
	v_add_f32_e32 v119, v119, v125
	v_add_f32_e32 v120, v120, v126
	v_add_f32_e32 v121, v121, v127
	v_add_f32_e32 v122, v122, v128
	v_add_f32_e32 v123, v123, v129
	ds_bpermute_b32 v124, v135, v118
	ds_bpermute_b32 v125, v135, v119
	ds_bpermute_b32 v126, v135, v120
	ds_bpermute_b32 v127, v135, v121
	ds_bpermute_b32 v128, v135, v122
	ds_bpermute_b32 v129, v135, v123
	s_waitcnt lgkmcnt(0)
	v_add_f32_e32 v118, v118, v124
	v_add_f32_e32 v119, v119, v125
	v_add_f32_e32 v120, v120, v126
	v_add_f32_e32 v121, v121, v127
	v_add_f32_e32 v122, v122, v128
	v_add_f32_e32 v123, v123, v129
	v_fmamk_f32 v118, v118, 0x3a800000, v136
	v_fmamk_f32 v119, v119, 0x3a800000, v136
	v_fmamk_f32 v120, v120, 0x3a800000, v136
	v_fmamk_f32 v121, v121, 0x3a800000, v136
	v_fmamk_f32 v122, v122, 0x3a800000, v136
	v_fmamk_f32 v123, v123, 0x3a800000, v136
	v_rsq_f32_e32 v118, v118
	v_rsq_f32_e32 v119, v119
	v_rsq_f32_e32 v120, v120
	v_rsq_f32_e32 v121, v121
	v_rsq_f32_e32 v122, v122
	v_rsq_f32_e32 v123, v123
	s_nop 0
	s_mov_b64 s[94:95], exec
	s_mov_b64 exec, 1
	s_lshl_b32 s67, s66, 2
	s_add_u32 s92, s42, s67
	s_addc_u32 s93, s43, 0
	s_add_u32 s92, s92, 0x6000000
	s_addc_u32 s93, s93, 0
	global_store_dword v137, v118, s[92:93]
	s_lshl_b32 s67, s97, 2
	s_add_u32 s92, s42, s67
	s_addc_u32 s93, s43, 0
	s_add_u32 s92, s92, 0x6000000
	s_addc_u32 s93, s93, 0
	global_store_dword v137, v119, s[92:93]
	s_lshl_b32 s67, s98, 2
	s_add_u32 s92, s42, s67
	s_addc_u32 s93, s43, 0
	s_add_u32 s92, s92, 0x6000000
	s_addc_u32 s93, s93, 0
	global_store_dword v137, v120, s[92:93]
	s_lshl_b32 s67, s96, 2
	s_add_u32 s92, s42, s67
	s_addc_u32 s93, s43, 0
	s_add_u32 s92, s92, 0x6000000
	s_addc_u32 s93, s93, 0
	global_store_dword v137, v121, s[92:93]
	s_lshl_b32 s67, s99, 2
	s_add_u32 s92, s42, s67
	s_addc_u32 s93, s43, 0
	s_add_u32 s92, s92, 0x6000000
	s_addc_u32 s93, s93, 0
	global_store_dword v137, v122, s[92:93]
	s_lshl_b32 s67, s58, 2
	s_add_u32 s92, s42, s67
	s_addc_u32 s93, s43, 0
	s_add_u32 s92, s92, 0x6000000
	s_addc_u32 s93, s93, 0
	global_store_dword v137, v123, s[92:93]
	s_mov_b64 exec, s[94:95]
	s_addk_i32 s56, 0x1800
	s_add_i32 s57, s57, -1
	s_cmp_lg_u32 s57, 0
	s_cbranch_scc1 .Lp01_pre_loop
	s_branch .Lp01_dec_done
.Lp01_fb:
	v_mov_b32_e32 v86, 0x358637bd
	v_mov_b32_e32 v87, 0
	v_lshlrev_b32_e32 v88, 4, v190
	v_xor_b32_e32 v80, 1, v190
	v_lshlrev_b32_e32 v80, 2, v80
	v_xor_b32_e32 v81, 2, v190
	v_lshlrev_b32_e32 v81, 2, v81
	v_xor_b32_e32 v82, 4, v190
	v_lshlrev_b32_e32 v82, 2, v82
	v_xor_b32_e32 v83, 8, v190
	v_lshlrev_b32_e32 v83, 2, v83
	v_xor_b32_e32 v84, 16, v190
	v_lshlrev_b32_e32 v84, 2, v84
	v_xor_b32_e32 v85, 32, v190
	v_lshlrev_b32_e32 v85, 2, v85
	s_add_i32 s66, s10, 0x800
